# fused norms: in-epilogue grid barrier replaced by a 4-workgroup sync per 256-row tile (the only sharers of a row sum)
# speedup vs baseline: 1.0068x; 1.0017x over previous
; __device__ __forceinline__ void rmsnorm_rows_f32(float* x, const float* gain, int nrows, int gw, int ngw, int lane) {
;     f32x4 gv[4];
; #pragma unroll
;     for (int j = 0; j < 4; ++j) gv[j] = *((const f32x4*)gain + lane + 64 * j);
; #pragma unroll 1
;     for (int r = gw; r < nrows; r += ngw) {
;         f32x4* xr = (f32x4*)(x + (size_t)r * D) + lane; f32x4 v[4]; float s = 0.f;
; #pragma unroll
;         for (int j = 0; j < 4; ++j) { v[j] = xr[64 * j]; s += (v[j].x * v[j].x + v[j].y * v[j].y) + (v[j].z * v[j].z + v[j].w * v[j].w); }
;         const float rs = rsqrtf(wave_sum(s) * (1.f / D) + 1e-6f);
; #pragma unroll
;         for (int j = 0; j < 4; ++j) xr[64 * j] = v[j] * rs * gv[j];
;     }
; }
;     __device__ __forceinline__ void emit(int row, int pn, int col0, float* v) const {
;     ...
;         case K_WO: case K_DN: {
;             const size_t o = ((size_t)grp * TG + row) * D + col0;
;             const f32x4 a0 = ldg<f32x4>(xi + o), a1 = ldg<f32x4>(xi + o + 4);
;             f32x4 r0, r1; r0.x = a0.x + v[0]; r0.y = a0.y + v[1]; r0.z = a0.z + v[2]; r0.w = a0.w + v[3]; r1.x = a1.x + v[4]; r1.y = a1.y + v[5]; r1.z = a1.z + v[6]; r1.w = a1.w + v[7];
;             stg<f32x4>(xo + o, r0); stg<f32x4>(xo + o + 4, r1);
;         } break;
.Lfn_nopart:
	s_waitcnt vmcnt(0)
	s_barrier
	v_readfirstlane_b32 s100, v192
	s_cmp_lg_u32 s100, 0
	s_cbranch_scc1 .Lfn_na
	s_lshl_b32 s100, s43, 2
	s_add_i32 s100, s100, 0x7800
	v_mov_b32_e32 v0, s100
	v_lshl_add_u64 v[134:135], v[132:133], 0, v[0:1]
	s_mov_b64 exec, 1
	flat_atomic_add v[134:135], v194
	s_mov_b64 exec, -1
.Lfn_na:
	v_mov_b32_e32 v0, 0x25940
	ds_read_b64 v[140:141], v0
	v_lshlrev_b32_e32 v0, 2, v203
	s_waitcnt lgkmcnt(0)
	v_readfirstlane_b32 s100, v140
	v_readfirstlane_b32 s101, v141
	s_nop 4
	global_load_dwordx4 v[144:147], v0, s[100:101]
	global_load_dwordx4 v[148:151], v0, s[100:101] offset:16
	global_load_dwordx4 v[152:155], v0, s[100:101] offset:512
	global_load_dwordx4 v[156:159], v0, s[100:101] offset:528
	v_readfirstlane_b32 s100, v192
	s_cmp_lg_u32 s100, 0
	s_cbranch_scc1 .Lfn_bw
	v_readlane_b32 s101, v255, 12
	s_cmpk_gt_u32 s101, 40
	s_cselect_b32 s101, 8, 4
	v_mov_b32_e32 v142, 0
.Lfn_spin:
	flat_load_dword v0, v[134:135] sc1
	s_waitcnt vmcnt(0) lgkmcnt(0)
	v_readfirstlane_b32 s100, v0
	s_cmp_ge_u32 s100, s101
	s_cbranch_scc1 .Lfn_rel
	s_sleep 2
	v_add_u32_e32 v142, 1, v142
	s_nop 0
	v_readfirstlane_b32 s100, v142
	s_cmpk_lt_u32 s100, 0x800
	s_cbranch_scc1 .Lfn_spin

;     __device__ __forceinline__ void emit(int row, int pn, int col0, float* v) const {
;     ...
;         case K_WO: case K_DN: {
;             const size_t o = ((size_t)grp * TG + row) * D + col0;
;             const f32x4 a0 = ldg<f32x4>(xi + o), a1 = ldg<f32x4>(xi + o + 4);
;             f32x4 r0, r1; r0.x = a0.x + v[0]; r0.y = a0.y + v[1]; r0.z = a0.z + v[2]; r0.w = a0.w + v[3]; r1.x = a1.x + v[4]; r1.y = a1.y + v[5]; r1.z = a1.z + v[6]; r1.w = a1.w + v[7];
;             stg<f32x4>(xo + o, r0); stg<f32x4>(xo + o + 4, r1);
;         } break;
.Lwo_nopart:
	s_waitcnt vmcnt(0)
	s_barrier
	v_readfirstlane_b32 s100, v192
	s_cmp_lg_u32 s100, 0
	s_cbranch_scc1 .Lwo_na
	s_lshl_b32 s100, s43, 2
	s_add_i32 s100, s100, 0x76c0
	v_mov_b32_e32 v0, s100
	v_lshl_add_u64 v[134:135], v[132:133], 0, v[0:1]
	s_mov_b64 exec, 1
	flat_atomic_add v[134:135], v194
	s_mov_b64 exec, -1

; __device__ __forceinline__ void rmsnorm_rows(const float* x, const float* gain, bf16_t* o, int nrows, int gw, int ngw, int lane) {
;     f32x4 gv[4];
; #pragma unroll
;     for (int j = 0; j < 4; ++j) gv[j] = ldg<f32x4>((const f32x4*)gain + lane + 64 * j);
;     __device__ __forceinline__ void emit(int row, int pn, int col0, float* v) const {
;     ...
;         case K_WO: case K_DN: {
;             const size_t o = ((size_t)grp * TG + row) * D + col0;
;             const f32x4 a0 = ldg<f32x4>(xi + o), a1 = ldg<f32x4>(xi + o + 4);
;             f32x4 r0, r1; r0.x = a0.x + v[0]; r0.y = a0.y + v[1]; r0.z = a0.z + v[2]; r0.w = a0.w + v[3]; r1.x = a1.x + v[4]; r1.y = a1.y + v[5]; r1.z = a1.z + v[6]; r1.w = a1.w + v[7];
;             stg<f32x4>(xo + o, r0); stg<f32x4>(xo + o + 4, r1);
;         } break;
.Lwo_l0:
	s_nop 4
	global_load_dwordx4 v[144:147], v0, s[100:101]
	global_load_dwordx4 v[148:151], v0, s[100:101] offset:16
	global_load_dwordx4 v[152:155], v0, s[100:101] offset:512
	global_load_dwordx4 v[156:159], v0, s[100:101] offset:528
	global_store_dwordx4 v182, v[128:131], s[66:67]
	global_store_dwordx4 v182, v[124:127], s[66:67] offset:16
	global_store_dwordx4 v182, v[120:123], s[66:67] offset:512
	global_store_dwordx4 v182, v[116:119], s[66:67] offset:528
	global_store_dwordx4 v183, v[112:115], s[66:67]
	global_store_dwordx4 v183, v[108:111], s[66:67] offset:16
	global_store_dwordx4 v183, v[104:107], s[66:67] offset:512
	global_store_dwordx4 v183, v[100:103], s[66:67] offset:528
	global_store_dwordx4 v184, v[96:99], s[66:67]
	global_store_dwordx4 v184, v[92:95], s[66:67] offset:16
	global_store_dwordx4 v184, v[88:91], s[66:67] offset:512
	global_store_dwordx4 v184, v[84:87], s[66:67] offset:528
	global_store_dwordx4 v185, v[80:83], s[66:67]
	global_store_dwordx4 v185, v[76:79], s[66:67] offset:16
	global_store_dwordx4 v185, v[72:75], s[66:67] offset:512
	global_store_dwordx4 v185, v[68:71], s[66:67] offset:528
	global_store_dwordx4 v190, v[64:67], s[66:67]
	global_store_dwordx4 v190, v[60:63], s[66:67] offset:16
	global_store_dwordx4 v190, v[56:59], s[66:67] offset:512
	global_store_dwordx4 v190, v[52:55], s[66:67] offset:528
	global_store_dwordx4 v191, v[48:51], s[66:67]
	global_store_dwordx4 v191, v[44:47], s[66:67] offset:16
	global_store_dwordx4 v191, v[40:43], s[66:67] offset:512
	global_store_dwordx4 v191, v[36:39], s[66:67] offset:528
	global_store_dwordx4 v200, v[32:35], s[66:67]
	global_store_dwordx4 v200, v[28:31], s[66:67] offset:16
	global_store_dwordx4 v200, v[24:27], s[66:67] offset:512
	global_store_dwordx4 v200, v[20:23], s[66:67] offset:528
	global_store_dwordx4 v201, v[16:19], s[66:67]
	global_store_dwordx4 v201, v[12:15], s[66:67] offset:16
	global_store_dwordx4 v201, v[8:11], s[66:67] offset:512
	global_store_dwordx4 v201, v[4:7], s[66:67] offset:528
	v_readfirstlane_b32 s100, v192
	s_cmp_lg_u32 s100, 0
	s_cbranch_scc1 .Lwo_bw
	v_readlane_b32 s101, v255, 12
	s_add_i32 s101, s101, 4
	s_mul_i32 s101, s101, 0x1556
	s_lshr_b32 s101, s101, 16
	s_lshl_b32 s101, s101, 2
	v_mov_b32_e32 v142, 0
